# fox unit prologue de-serialisation: Q-fragment and CLOC loads issued before the TOT scan (one global round trip instead of three)
# baseline (speedup 1.0000x reference)
.LBB0_655:
	s_or_b64 exec, exec, s[2:3]
	v_mov_b32_e32 v2, s18
	s_waitcnt lgkmcnt(0)
	s_barrier
	ds_read_b32 v2, v2
	s_movk_i32 s2, 0x7f
	s_waitcnt lgkmcnt(0)
	v_cmp_lt_i32_e32 vcc, s2, v2
	v_readfirstlane_b32 s11, v2
	s_mov_b64 s[2:3], -1
	s_cbranch_vccnz .LBB0_652
	s_and_b32 s10, s11, 7
	s_lshl_b32 s2, s11, 5
	s_and_b32 s58, s2, 0xffffff00
	s_sub_i32 s11, 0x1000, s58
	v_readlane_b32 s2, v253, 63
	s_sub_i32 s23, 0xf00, s58
	v_readlane_b32 s3, v252, 0
	v_add_u32_e32 v148, s23, v189
	s_lshl_b32 s14, s10, 7
	v_mov_b64_e32 v[146:147], s[2:3]
	s_movk_i32 s2, 0x1800
	v_mad_i64_i32 v[146:147], s[2:3], v148, s2, v[146:147]
	v_lshl_add_u64 v[146:147], v[146:147], 0, s[14:15]
	v_lshl_add_u64 v[146:147], v[146:147], 0, v[174:175]
	global_load_dwordx4 v[114:117], v[146:147], off
	global_load_dwordx4 v[106:109], v[146:147], off offset:32
	global_load_dwordx4 v[102:105], v[146:147], off offset:64
	global_load_dwordx4 v[98:101], v[146:147], off offset:96
	v_cmp_gt_i32_e32 vcc, s11, v0
	s_and_saveexec_b64 s[2:3], vcc
	s_cbranch_execz .Ldk_p1_done
	s_lshl_b32 s14, s10, 2
	v_lshl_add_u64 v[2:3], v[186:187], 0, s[14:15]
	v_mov_b32_e32 v6, v0
	s_mov_b64 s[12:13], 0x4000
	global_load_dword v130, v[2:3], off
	v_add_u32_e32 v6, 0x200, v6
	v_cmp_gt_i32_e32 vcc, s11, v6
	v_lshl_add_u64 v[2:3], v[2:3], 0, s[12:13]
	s_nop 1
	s_and_b64 exec, exec, vcc
	s_cbranch_execz .Ldk_p1_done
	global_load_dword v131, v[2:3], off
	v_add_u32_e32 v6, 0x200, v6
	v_cmp_gt_i32_e32 vcc, s11, v6
	v_lshl_add_u64 v[2:3], v[2:3], 0, s[12:13]
	s_nop 1
	s_and_b64 exec, exec, vcc
	s_cbranch_execz .Ldk_p1_done
	global_load_dword v132, v[2:3], off
	v_add_u32_e32 v6, 0x200, v6
	v_cmp_gt_i32_e32 vcc, s11, v6
	v_lshl_add_u64 v[2:3], v[2:3], 0, s[12:13]
	s_nop 1
	s_and_b64 exec, exec, vcc
	s_cbranch_execz .Ldk_p1_done
	global_load_dword v133, v[2:3], off
	v_add_u32_e32 v6, 0x200, v6
	v_cmp_gt_i32_e32 vcc, s11, v6
	v_lshl_add_u64 v[2:3], v[2:3], 0, s[12:13]
	s_nop 1
	s_and_b64 exec, exec, vcc
	s_cbranch_execz .Ldk_p1_done
	global_load_dword v134, v[2:3], off
	v_add_u32_e32 v6, 0x200, v6
	v_cmp_gt_i32_e32 vcc, s11, v6
	v_lshl_add_u64 v[2:3], v[2:3], 0, s[12:13]
	s_nop 1
	s_and_b64 exec, exec, vcc
	s_cbranch_execz .Ldk_p1_done
	global_load_dword v135, v[2:3], off
	v_add_u32_e32 v6, 0x200, v6
	v_cmp_gt_i32_e32 vcc, s11, v6
	v_lshl_add_u64 v[2:3], v[2:3], 0, s[12:13]
	s_nop 1
	s_and_b64 exec, exec, vcc
	s_cbranch_execz .Ldk_p1_done
	global_load_dword v136, v[2:3], off
	v_add_u32_e32 v6, 0x200, v6
	v_cmp_gt_i32_e32 vcc, s11, v6
	v_lshl_add_u64 v[2:3], v[2:3], 0, s[12:13]
	s_nop 1
	s_and_b64 exec, exec, vcc
	s_cbranch_execz .Ldk_p1_done
	global_load_dword v137, v[2:3], off
.Ldk_p1_done:
	s_or_b64 exec, exec, s[2:3]
	s_mov_b64 s[2:3], exec
	v_readlane_b32 s8, v252, 16
	v_readlane_b32 s9, v252, 17
	s_and_b64 s[8:9], s[2:3], s[8:9]
	s_mov_b64 exec, s[8:9]
	s_cbranch_execz .LBB0_661
	v_mov_b32_e32 v2, 0
	s_and_saveexec_b64 s[8:9], s[4:5]
	s_cbranch_execz .LBB0_659
	v_or_b32_e32 v2, s10, v185
	v_readlane_b32 s12, v252, 18
	v_ashrrev_i32_e32 v3, 31, v2
	v_readlane_b32 s13, v252, 19
	s_nop 1
	v_lshl_add_u64 v[2:3], v[2:3], 2, s[12:13]
	global_load_dword v2, v[2:3], off

.LBB0_661:
	s_or_b64 exec, exec, s[2:3]
	s_waitcnt lgkmcnt(0)
	v_cmp_gt_i32_e32 vcc, s11, v0
	s_waitcnt lgkmcnt(0)
	s_barrier
	s_and_saveexec_b64 s[2:3], vcc
	s_cbranch_execz .LBB0_664
	v_mov_b32_e32 v4, v227
	v_mov_b32_e32 v5, v1
	v_mov_b32_e32 v6, v0
	ds_read_b32 v138, v4
	ds_read_b32 v139, v4 offset:16
	ds_read_b32 v140, v4 offset:32
	ds_read_b32 v141, v4 offset:48
	ds_read_b32 v142, v4 offset:64
	ds_read_b32 v143, v4 offset:80
	ds_read_b32 v144, v4 offset:96
	ds_read_b32 v145, v4 offset:112
	s_waitcnt vmcnt(0) lgkmcnt(0)
	v_add_f32_e32 v7, v138, v130
	v_mul_f32_e32 v7, 0xbfb8aa3b, v7
	ds_write_b32 v5, v7
	v_add_u32_e32 v6, 0x200, v6
	v_cmp_gt_i32_e32 vcc, s11, v6
	v_add_u32_e32 v5, 0x800, v5
	s_nop 1
	s_and_b64 exec, exec, vcc
	s_cbranch_execz .Ldk_done
	v_add_f32_e32 v7, v139, v131
	v_mul_f32_e32 v7, 0xbfb8aa3b, v7
	ds_write_b32 v5, v7
	v_add_u32_e32 v6, 0x200, v6
	v_cmp_gt_i32_e32 vcc, s11, v6
	v_add_u32_e32 v5, 0x800, v5
	s_nop 1
	s_and_b64 exec, exec, vcc
	s_cbranch_execz .Ldk_done
	v_add_f32_e32 v7, v140, v132
	v_mul_f32_e32 v7, 0xbfb8aa3b, v7
	ds_write_b32 v5, v7
	v_add_u32_e32 v6, 0x200, v6
	v_cmp_gt_i32_e32 vcc, s11, v6
	v_add_u32_e32 v5, 0x800, v5
	s_nop 1
	s_and_b64 exec, exec, vcc
	s_cbranch_execz .Ldk_done
	v_add_f32_e32 v7, v141, v133
	v_mul_f32_e32 v7, 0xbfb8aa3b, v7
	ds_write_b32 v5, v7
	v_add_u32_e32 v6, 0x200, v6
	v_cmp_gt_i32_e32 vcc, s11, v6
	v_add_u32_e32 v5, 0x800, v5
	s_nop 1
	s_and_b64 exec, exec, vcc
	s_cbranch_execz .Ldk_done
	v_add_f32_e32 v7, v142, v134
	v_mul_f32_e32 v7, 0xbfb8aa3b, v7
	ds_write_b32 v5, v7
	v_add_u32_e32 v6, 0x200, v6
	v_cmp_gt_i32_e32 vcc, s11, v6
	v_add_u32_e32 v5, 0x800, v5
	s_nop 1
	s_and_b64 exec, exec, vcc
	s_cbranch_execz .Ldk_done
	v_add_f32_e32 v7, v143, v135
	v_mul_f32_e32 v7, 0xbfb8aa3b, v7
	ds_write_b32 v5, v7
	v_add_u32_e32 v6, 0x200, v6
	v_cmp_gt_i32_e32 vcc, s11, v6
	v_add_u32_e32 v5, 0x800, v5
	s_nop 1
	s_and_b64 exec, exec, vcc
	s_cbranch_execz .Ldk_done
	v_add_f32_e32 v7, v144, v136
	v_mul_f32_e32 v7, 0xbfb8aa3b, v7
	ds_write_b32 v5, v7
	v_add_u32_e32 v6, 0x200, v6
	v_cmp_gt_i32_e32 vcc, s11, v6
	v_add_u32_e32 v5, 0x800, v5
	s_nop 1
	s_and_b64 exec, exec, vcc
	s_cbranch_execz .Ldk_done
	v_add_f32_e32 v7, v145, v137
	v_mul_f32_e32 v7, 0xbfb8aa3b, v7
	ds_write_b32 v5, v7
.Ldk_done:
.LBB0_664:
	s_or_b64 exec, exec, s[2:3]
	v_readlane_b32 s2, v253, 63
	s_sub_i32 s23, 0xf00, s58
	v_readlane_b32 s3, v252, 0
	s_lshl_b32 s14, s10, 7
	s_movk_i32 s2, 0x1800
	s_waitcnt vmcnt(0) lgkmcnt(0)
	s_barrier
	s_lshr_b32 s29, s11, 6
	v_cmp_le_u32_e32 vcc, s29, v190
	s_and_saveexec_b64 s[2:3], vcc
	s_xor_b64 s[2:3], exec, s[2:3]
	s_sub_i32 s11, 0, s58
	s_or_saveexec_b64 s[2:3], s[2:3]
	s_mov_b64 s[8:9], 0
	v_mov_b32_e32 v2, s11
	s_xor_b64 exec, exec, s[2:3]
	s_cbranch_execz .LBB0_668
	s_lshl_b32 s8, s58, 2
	s_sub_i32 s8, 0, s8
	v_mov_b32_e32 v2, s8
	ds_read_b32 v2, v2 offset:64512
	ds_read_b32 v3, v232 offset:49660
	s_mov_b32 s9, 0x43000000
	s_sub_i32 s8, 0, s58
	s_waitcnt lgkmcnt(0)
	v_sub_f32_e32 v2, v2, v3
	v_cmp_lt_f32_e32 vcc, s9, v2
	v_mov_b32_e32 v2, s8
	s_and_b64 s[8:9], vcc, exec
